# saddr K-loop plus: B-fragment ds_reads use one per-tile base VGPR with immediate offsets (no per-segment address SALU/VALU), m0 values formed by single s_add_i32 with literal
# speedup vs baseline: 1.0060x; 1.0060x over previous
.Lprio_done:
	s_add_u32 s0, s90, 0x80
	s_addc_u32 s1, s91, 0
	s_add_u32 s11, s2, 0x100
	s_addc_u32 s24, s3, 0
	s_mov_b32 s2, 0
	s_add_i32 s90, s2, 2
	s_add_u32 s82, s0, 0x80
	s_addc_u32 s3, s1, 0
	s_cmp_eq_u32 s62, s2
	s_cselect_b32 s3, s23, s3
	s_cselect_b32 s2, s22, s82
	s_cselect_b32 vcc_hi, s13, s24
	s_cselect_b32 vcc_lo, s12, s11
	v_add_u32_e32 v170, 0x10000, v157
	v_add_u32_e32 v232, s26, v150
	v_add_u32_e32 v233, s26, v154
	v_add_u32_e32 v234, s58, v148
	v_add_u32_e32 v235, s58, v152
	ds_read_b128 v[128:131], v170
	ds_read_b128 v[132:135], v170 offset:1024
	ds_read_b128 v[136:139], v170 offset:2048
	ds_read_b128 v[140:143], v170 offset:3072
	ds_read_b128 v[166:169], v170 offset:16384
	ds_read_b128 v[176:179], v170 offset:17408
	ds_read_b128 v[180:183], v170 offset:18432
	ds_read_b128 v[184:187], v170 offset:19456
	s_add_i32 m0, s37, 0xc000
	ds_read_b128 v[188:191], v242
	ds_read_b128 v[192:195], v242 offset:1024
	ds_read_b128 v[196:199], v242 offset:2048
	ds_read_b128 v[200:203], v242 offset:3072
	ds_read_b128 v[204:207], v242 offset:4096
	ds_read_b128 v[208:211], v242 offset:5120
	ds_read_b128 v[212:215], v242 offset:6144
	ds_read_b128 v[216:219], v242 offset:7168
	global_load_lds_dwordx4 v160, s[0:1]
	s_add_i32 m0, s37, 0xe000
	s_nop 0
	global_load_lds_dwordx4 v162, s[0:1]
	s_waitcnt vmcnt(8) lgkmcnt(0)
	s_barrier
	v_mfma_f32_16x16x32_bf16 v[124:127], v[128:131], v[188:191], 0
	v_mfma_f32_16x16x32_bf16 v[120:123], v[136:139], v[188:191], 0
	v_mfma_f32_16x16x32_bf16 v[108:111], v[128:131], v[196:199], 0
	v_mfma_f32_16x16x32_bf16 v[104:107], v[136:139], v[196:199], 0
	v_mfma_f32_16x16x32_bf16 v[92:95], v[128:131], v[204:207], 0
	v_mfma_f32_16x16x32_bf16 v[88:91], v[136:139], v[204:207], 0
	v_mfma_f32_16x16x32_bf16 v[76:79], v[128:131], v[212:215], 0
	v_mfma_f32_16x16x32_bf16 v[72:75], v[136:139], v[212:215], 0
	v_mfma_f32_16x16x32_bf16 v[124:127], v[132:135], v[192:195], v[124:127]
	v_mfma_f32_16x16x32_bf16 v[120:123], v[140:143], v[192:195], v[120:123]
	v_mfma_f32_16x16x32_bf16 v[108:111], v[132:135], v[200:203], v[108:111]
	v_mfma_f32_16x16x32_bf16 v[104:107], v[140:143], v[200:203], v[104:107]
	v_mfma_f32_16x16x32_bf16 v[92:95], v[132:135], v[208:211], v[92:95]
	v_mfma_f32_16x16x32_bf16 v[88:91], v[140:143], v[208:211], v[88:91]
	v_mfma_f32_16x16x32_bf16 v[76:79], v[132:135], v[216:219], v[76:79]
	v_mfma_f32_16x16x32_bf16 v[72:75], v[140:143], v[216:219], v[72:75]
	v_mfma_f32_16x16x32_bf16 v[116:119], v[166:169], v[188:191], 0
	v_mfma_f32_16x16x32_bf16 v[112:115], v[180:183], v[188:191], 0
	v_mfma_f32_16x16x32_bf16 v[100:103], v[166:169], v[196:199], 0
	v_mfma_f32_16x16x32_bf16 v[96:99], v[180:183], v[196:199], 0
	v_mfma_f32_16x16x32_bf16 v[84:87], v[166:169], v[204:207], 0
	v_mfma_f32_16x16x32_bf16 v[80:83], v[180:183], v[204:207], 0
	v_mfma_f32_16x16x32_bf16 v[68:71], v[166:169], v[212:215], 0
	v_mfma_f32_16x16x32_bf16 v[64:67], v[180:183], v[212:215], 0
	v_mfma_f32_16x16x32_bf16 v[116:119], v[176:179], v[192:195], v[116:119]
	v_mfma_f32_16x16x32_bf16 v[112:115], v[184:187], v[192:195], v[112:115]
	v_mfma_f32_16x16x32_bf16 v[100:103], v[176:179], v[200:203], v[100:103]
	v_mfma_f32_16x16x32_bf16 v[96:99], v[184:187], v[200:203], v[96:99]
	v_mfma_f32_16x16x32_bf16 v[84:87], v[176:179], v[208:211], v[84:87]
	v_mfma_f32_16x16x32_bf16 v[80:83], v[184:187], v[208:211], v[80:83]
	v_mfma_f32_16x16x32_bf16 v[68:71], v[176:179], v[216:219], v[68:71]
	v_mfma_f32_16x16x32_bf16 v[64:67], v[184:187], v[216:219], v[64:67]
	s_barrier
	s_add_i32 m0, s36, 0x10000
	ds_read_b128 v[188:191], v242 offset:16384
	ds_read_b128 v[192:195], v242 offset:17408
	ds_read_b128 v[196:199], v242 offset:18432
	ds_read_b128 v[200:203], v242 offset:19456
	ds_read_b128 v[204:207], v242 offset:20480
	ds_read_b128 v[208:211], v242 offset:21504
	ds_read_b128 v[212:215], v242 offset:22528
	ds_read_b128 v[216:219], v242 offset:23552
	global_load_lds_dwordx4 v150, vcc
	s_add_i32 m0, s36, 0x12000
	s_nop 0
	global_load_lds_dwordx4 v154, vcc
	s_add_i32 m0, s36, 0x14000
	s_nop 0
	global_load_lds_dwordx4 v232, vcc
	s_add_i32 m0, s36, 0x16000
	s_nop 0
	global_load_lds_dwordx4 v233, vcc
	s_mov_b32 m0, s37
	s_nop 0
	global_load_lds_dwordx4 v148, s[2:3]
	s_mov_b32 m0, s42
	s_nop 0
	global_load_lds_dwordx4 v152, s[2:3]
	s_waitcnt vmcnt(8) lgkmcnt(0)
	s_barrier
	v_mfma_f32_16x16x32_bf16 v[60:63], v[128:131], v[188:191], 0
	v_mfma_f32_16x16x32_bf16 v[56:59], v[136:139], v[188:191], 0
	v_mfma_f32_16x16x32_bf16 v[44:47], v[128:131], v[196:199], 0
	v_mfma_f32_16x16x32_bf16 v[40:43], v[136:139], v[196:199], 0
	v_mfma_f32_16x16x32_bf16 v[28:31], v[128:131], v[204:207], 0
	v_mfma_f32_16x16x32_bf16 v[24:27], v[136:139], v[204:207], 0
	v_mfma_f32_16x16x32_bf16 v[12:15], v[128:131], v[212:215], 0
	v_mfma_f32_16x16x32_bf16 v[8:11], v[136:139], v[212:215], 0
	v_mfma_f32_16x16x32_bf16 v[60:63], v[132:135], v[192:195], v[60:63]
	v_mfma_f32_16x16x32_bf16 v[56:59], v[140:143], v[192:195], v[56:59]
	v_mfma_f32_16x16x32_bf16 v[44:47], v[132:135], v[200:203], v[44:47]
	v_mfma_f32_16x16x32_bf16 v[40:43], v[140:143], v[200:203], v[40:43]
	v_mfma_f32_16x16x32_bf16 v[28:31], v[132:135], v[208:211], v[28:31]
	v_mfma_f32_16x16x32_bf16 v[24:27], v[140:143], v[208:211], v[24:27]
	v_mfma_f32_16x16x32_bf16 v[12:15], v[132:135], v[216:219], v[12:15]
	v_mfma_f32_16x16x32_bf16 v[8:11], v[140:143], v[216:219], v[8:11]
	v_mfma_f32_16x16x32_bf16 v[52:55], v[166:169], v[188:191], 0
	v_mfma_f32_16x16x32_bf16 v[48:51], v[180:183], v[188:191], 0
	v_mfma_f32_16x16x32_bf16 v[36:39], v[166:169], v[196:199], 0
	v_mfma_f32_16x16x32_bf16 v[32:35], v[180:183], v[196:199], 0
	v_mfma_f32_16x16x32_bf16 v[20:23], v[166:169], v[204:207], 0
	v_mfma_f32_16x16x32_bf16 v[16:19], v[180:183], v[204:207], 0
	v_mfma_f32_16x16x32_bf16 v[4:7], v[166:169], v[212:215], 0
	v_mfma_f32_16x16x32_bf16 v[0:3], v[180:183], v[212:215], 0
	v_mfma_f32_16x16x32_bf16 v[52:55], v[176:179], v[192:195], v[52:55]
	v_mfma_f32_16x16x32_bf16 v[48:51], v[184:187], v[192:195], v[48:51]
	v_mfma_f32_16x16x32_bf16 v[36:39], v[176:179], v[200:203], v[36:39]
	v_mfma_f32_16x16x32_bf16 v[32:35], v[184:187], v[200:203], v[32:35]
	v_mfma_f32_16x16x32_bf16 v[20:23], v[176:179], v[208:211], v[20:23]
	v_mfma_f32_16x16x32_bf16 v[16:19], v[184:187], v[208:211], v[16:19]
	v_mfma_f32_16x16x32_bf16 v[4:7], v[176:179], v[216:219], v[4:7]
	v_mfma_f32_16x16x32_bf16 v[0:3], v[184:187], v[216:219], v[0:3]
	s_barrier
	ds_read_b128 v[128:131], v170 offset:32768
	ds_read_b128 v[132:135], v170 offset:33792
	ds_read_b128 v[136:139], v170 offset:34816
	ds_read_b128 v[140:143], v170 offset:35840
	ds_read_b128 v[166:169], v170 offset:49152
	ds_read_b128 v[176:179], v170 offset:50176
	ds_read_b128 v[180:183], v170 offset:51200
	ds_read_b128 v[184:187], v170 offset:52224
	s_mov_b32 m0, s43
	ds_read_b128 v[188:191], v242 offset:32768
	ds_read_b128 v[192:195], v242 offset:33792
	ds_read_b128 v[196:199], v242 offset:34816
	ds_read_b128 v[200:203], v242 offset:35840
	ds_read_b128 v[204:207], v242 offset:36864
	ds_read_b128 v[208:211], v242 offset:37888
	ds_read_b128 v[212:215], v242 offset:38912
	ds_read_b128 v[216:219], v242 offset:39936
	global_load_lds_dwordx4 v234, s[2:3]
	s_mov_b32 m0, s16
	s_nop 0
	global_load_lds_dwordx4 v235, s[2:3]
	s_waitcnt vmcnt(8) lgkmcnt(0)
	s_barrier
	v_mfma_f32_16x16x32_bf16 v[124:127], v[128:131], v[188:191], v[124:127]
	v_mfma_f32_16x16x32_bf16 v[120:123], v[136:139], v[188:191], v[120:123]
	v_mfma_f32_16x16x32_bf16 v[108:111], v[128:131], v[196:199], v[108:111]
	v_mfma_f32_16x16x32_bf16 v[104:107], v[136:139], v[196:199], v[104:107]
	v_mfma_f32_16x16x32_bf16 v[92:95], v[128:131], v[204:207], v[92:95]
	v_mfma_f32_16x16x32_bf16 v[88:91], v[136:139], v[204:207], v[88:91]
	v_mfma_f32_16x16x32_bf16 v[76:79], v[128:131], v[212:215], v[76:79]
	v_mfma_f32_16x16x32_bf16 v[72:75], v[136:139], v[212:215], v[72:75]
	v_mfma_f32_16x16x32_bf16 v[124:127], v[132:135], v[192:195], v[124:127]
	v_mfma_f32_16x16x32_bf16 v[120:123], v[140:143], v[192:195], v[120:123]
	v_mfma_f32_16x16x32_bf16 v[108:111], v[132:135], v[200:203], v[108:111]
	v_mfma_f32_16x16x32_bf16 v[104:107], v[140:143], v[200:203], v[104:107]
	v_mfma_f32_16x16x32_bf16 v[92:95], v[132:135], v[208:211], v[92:95]
	v_mfma_f32_16x16x32_bf16 v[88:91], v[140:143], v[208:211], v[88:91]
	v_mfma_f32_16x16x32_bf16 v[76:79], v[132:135], v[216:219], v[76:79]
	v_mfma_f32_16x16x32_bf16 v[72:75], v[140:143], v[216:219], v[72:75]
	v_mfma_f32_16x16x32_bf16 v[116:119], v[166:169], v[188:191], v[116:119]
	v_mfma_f32_16x16x32_bf16 v[112:115], v[180:183], v[188:191], v[112:115]
	v_mfma_f32_16x16x32_bf16 v[100:103], v[166:169], v[196:199], v[100:103]
	v_mfma_f32_16x16x32_bf16 v[96:99], v[180:183], v[196:199], v[96:99]
	v_mfma_f32_16x16x32_bf16 v[84:87], v[166:169], v[204:207], v[84:87]
	v_mfma_f32_16x16x32_bf16 v[80:83], v[180:183], v[204:207], v[80:83]
	v_mfma_f32_16x16x32_bf16 v[68:71], v[166:169], v[212:215], v[68:71]
	v_mfma_f32_16x16x32_bf16 v[64:67], v[180:183], v[212:215], v[64:67]
	v_mfma_f32_16x16x32_bf16 v[116:119], v[176:179], v[192:195], v[116:119]
	v_mfma_f32_16x16x32_bf16 v[112:115], v[184:187], v[192:195], v[112:115]
	v_mfma_f32_16x16x32_bf16 v[100:103], v[176:179], v[200:203], v[100:103]
	v_mfma_f32_16x16x32_bf16 v[96:99], v[184:187], v[200:203], v[96:99]
	v_mfma_f32_16x16x32_bf16 v[84:87], v[176:179], v[208:211], v[84:87]
	v_mfma_f32_16x16x32_bf16 v[80:83], v[184:187], v[208:211], v[80:83]
	v_mfma_f32_16x16x32_bf16 v[68:71], v[176:179], v[216:219], v[68:71]
	v_mfma_f32_16x16x32_bf16 v[64:67], v[184:187], v[216:219], v[64:67]
	s_barrier
	s_add_i32 m0, s36, 0x18000
	ds_read_b128 v[188:191], v242 offset:49152
	ds_read_b128 v[192:195], v242 offset:50176
	ds_read_b128 v[196:199], v242 offset:51200
	ds_read_b128 v[200:203], v242 offset:52224
	ds_read_b128 v[204:207], v242 offset:53248
	ds_read_b128 v[208:211], v242 offset:54272
	ds_read_b128 v[212:215], v242 offset:55296
	ds_read_b128 v[216:219], v242 offset:56320
	s_add_u32 vcc_lo, vcc_lo, 0x80
	s_addc_u32 vcc_hi, vcc_hi, 0
	global_load_lds_dwordx4 v150, vcc
	s_add_i32 m0, s36, 0x1a000
	s_add_u32 s2, s2, 0x80
	s_addc_u32 s3, s3, 0
	global_load_lds_dwordx4 v154, vcc
	s_add_i32 m0, s36, 0x1c000
	s_nop 0
	global_load_lds_dwordx4 v232, vcc
	s_add_i32 m0, s36, 0x1e000
	s_add_u32 s0, s0, 0x100
	s_addc_u32 s1, s1, 0
	global_load_lds_dwordx4 v233, vcc
	s_mov_b32 m0, s63
	s_add_u32 s11, s11, 0x100
	s_addc_u32 s24, s24, 0
	global_load_lds_dwordx4 v148, s[2:3]
	s_mov_b32 m0, s18
	s_nop 0
	global_load_lds_dwordx4 v152, s[2:3]
	s_waitcnt vmcnt(8) lgkmcnt(0)
	s_barrier
	v_mfma_f32_16x16x32_bf16 v[60:63], v[128:131], v[188:191], v[60:63]
	v_mfma_f32_16x16x32_bf16 v[56:59], v[136:139], v[188:191], v[56:59]
	v_mfma_f32_16x16x32_bf16 v[44:47], v[128:131], v[196:199], v[44:47]
	v_mfma_f32_16x16x32_bf16 v[40:43], v[136:139], v[196:199], v[40:43]
	v_mfma_f32_16x16x32_bf16 v[28:31], v[128:131], v[204:207], v[28:31]
	v_mfma_f32_16x16x32_bf16 v[24:27], v[136:139], v[204:207], v[24:27]
	v_mfma_f32_16x16x32_bf16 v[12:15], v[128:131], v[212:215], v[12:15]
	v_mfma_f32_16x16x32_bf16 v[8:11], v[136:139], v[212:215], v[8:11]
	v_mfma_f32_16x16x32_bf16 v[60:63], v[132:135], v[192:195], v[60:63]
	v_mfma_f32_16x16x32_bf16 v[56:59], v[140:143], v[192:195], v[56:59]
	v_mfma_f32_16x16x32_bf16 v[44:47], v[132:135], v[200:203], v[44:47]
	v_mfma_f32_16x16x32_bf16 v[40:43], v[140:143], v[200:203], v[40:43]
	v_mfma_f32_16x16x32_bf16 v[28:31], v[132:135], v[208:211], v[28:31]
	v_mfma_f32_16x16x32_bf16 v[24:27], v[140:143], v[208:211], v[24:27]
	v_mfma_f32_16x16x32_bf16 v[12:15], v[132:135], v[216:219], v[12:15]
	v_mfma_f32_16x16x32_bf16 v[8:11], v[140:143], v[216:219], v[8:11]
	v_mfma_f32_16x16x32_bf16 v[52:55], v[166:169], v[188:191], v[52:55]
	v_mfma_f32_16x16x32_bf16 v[48:51], v[180:183], v[188:191], v[48:51]
	v_mfma_f32_16x16x32_bf16 v[36:39], v[166:169], v[196:199], v[36:39]
	v_mfma_f32_16x16x32_bf16 v[32:35], v[180:183], v[196:199], v[32:35]
	v_mfma_f32_16x16x32_bf16 v[20:23], v[166:169], v[204:207], v[20:23]
	v_mfma_f32_16x16x32_bf16 v[16:19], v[180:183], v[204:207], v[16:19]
	v_mfma_f32_16x16x32_bf16 v[4:7], v[166:169], v[212:215], v[4:7]
	v_mfma_f32_16x16x32_bf16 v[0:3], v[180:183], v[212:215], v[0:3]
	v_mfma_f32_16x16x32_bf16 v[52:55], v[176:179], v[192:195], v[52:55]
	v_mfma_f32_16x16x32_bf16 v[48:51], v[184:187], v[192:195], v[48:51]
	v_mfma_f32_16x16x32_bf16 v[36:39], v[176:179], v[200:203], v[36:39]
	v_mfma_f32_16x16x32_bf16 v[32:35], v[184:187], v[200:203], v[32:35]
	v_mfma_f32_16x16x32_bf16 v[20:23], v[176:179], v[208:211], v[20:23]
	v_mfma_f32_16x16x32_bf16 v[16:19], v[184:187], v[208:211], v[16:19]
	v_mfma_f32_16x16x32_bf16 v[4:7], v[176:179], v[216:219], v[4:7]
	v_mfma_f32_16x16x32_bf16 v[0:3], v[184:187], v[216:219], v[0:3]
	s_barrier
	s_cmp_ge_u32 s90, s60
	s_mov_b32 s2, s90
	s_cbranch_scc1 .LBB0_297
.LBB0_295:
	s_add_i32 s90, s2, 2
	s_add_u32 s82, s0, 0x80
	s_addc_u32 s3, s1, 0
	s_cmp_eq_u32 s62, s2
	s_cselect_b32 s3, s23, s3
	s_cselect_b32 s2, s22, s82
	s_cselect_b32 vcc_hi, s13, s24
	s_cselect_b32 vcc_lo, s12, s11
	ds_read_b128 v[128:131], v170
	ds_read_b128 v[132:135], v170 offset:1024
	ds_read_b128 v[136:139], v170 offset:2048
	ds_read_b128 v[140:143], v170 offset:3072
	ds_read_b128 v[166:169], v170 offset:16384
	ds_read_b128 v[176:179], v170 offset:17408
	ds_read_b128 v[180:183], v170 offset:18432
	ds_read_b128 v[184:187], v170 offset:19456
	s_add_i32 m0, s37, 0xc000
	ds_read_b128 v[188:191], v242
	ds_read_b128 v[192:195], v242 offset:1024
	ds_read_b128 v[196:199], v242 offset:2048
	ds_read_b128 v[200:203], v242 offset:3072
	ds_read_b128 v[204:207], v242 offset:4096
	ds_read_b128 v[208:211], v242 offset:5120
	ds_read_b128 v[212:215], v242 offset:6144
	ds_read_b128 v[216:219], v242 offset:7168
	global_load_lds_dwordx4 v160, s[0:1]
	s_add_i32 m0, s37, 0xe000
	s_nop 0
	global_load_lds_dwordx4 v162, s[0:1]
	s_waitcnt vmcnt(8) lgkmcnt(0)
	s_barrier
	v_mfma_f32_16x16x32_bf16 v[124:127], v[128:131], v[188:191], v[124:127]
	v_mfma_f32_16x16x32_bf16 v[120:123], v[136:139], v[188:191], v[120:123]
	v_mfma_f32_16x16x32_bf16 v[108:111], v[128:131], v[196:199], v[108:111]
	v_mfma_f32_16x16x32_bf16 v[104:107], v[136:139], v[196:199], v[104:107]
	v_mfma_f32_16x16x32_bf16 v[92:95], v[128:131], v[204:207], v[92:95]
	v_mfma_f32_16x16x32_bf16 v[88:91], v[136:139], v[204:207], v[88:91]
	v_mfma_f32_16x16x32_bf16 v[76:79], v[128:131], v[212:215], v[76:79]
	v_mfma_f32_16x16x32_bf16 v[72:75], v[136:139], v[212:215], v[72:75]
	v_mfma_f32_16x16x32_bf16 v[124:127], v[132:135], v[192:195], v[124:127]
	v_mfma_f32_16x16x32_bf16 v[120:123], v[140:143], v[192:195], v[120:123]
	v_mfma_f32_16x16x32_bf16 v[108:111], v[132:135], v[200:203], v[108:111]
	v_mfma_f32_16x16x32_bf16 v[104:107], v[140:143], v[200:203], v[104:107]
	v_mfma_f32_16x16x32_bf16 v[92:95], v[132:135], v[208:211], v[92:95]
	v_mfma_f32_16x16x32_bf16 v[88:91], v[140:143], v[208:211], v[88:91]
	v_mfma_f32_16x16x32_bf16 v[76:79], v[132:135], v[216:219], v[76:79]
	v_mfma_f32_16x16x32_bf16 v[72:75], v[140:143], v[216:219], v[72:75]
	v_mfma_f32_16x16x32_bf16 v[116:119], v[166:169], v[188:191], v[116:119]
	v_mfma_f32_16x16x32_bf16 v[112:115], v[180:183], v[188:191], v[112:115]
	v_mfma_f32_16x16x32_bf16 v[100:103], v[166:169], v[196:199], v[100:103]
	v_mfma_f32_16x16x32_bf16 v[96:99], v[180:183], v[196:199], v[96:99]
	v_mfma_f32_16x16x32_bf16 v[84:87], v[166:169], v[204:207], v[84:87]
	v_mfma_f32_16x16x32_bf16 v[80:83], v[180:183], v[204:207], v[80:83]
	v_mfma_f32_16x16x32_bf16 v[68:71], v[166:169], v[212:215], v[68:71]
	v_mfma_f32_16x16x32_bf16 v[64:67], v[180:183], v[212:215], v[64:67]
	v_mfma_f32_16x16x32_bf16 v[116:119], v[176:179], v[192:195], v[116:119]
	v_mfma_f32_16x16x32_bf16 v[112:115], v[184:187], v[192:195], v[112:115]
	v_mfma_f32_16x16x32_bf16 v[100:103], v[176:179], v[200:203], v[100:103]
	v_mfma_f32_16x16x32_bf16 v[96:99], v[184:187], v[200:203], v[96:99]
	v_mfma_f32_16x16x32_bf16 v[84:87], v[176:179], v[208:211], v[84:87]
	v_mfma_f32_16x16x32_bf16 v[80:83], v[184:187], v[208:211], v[80:83]
	v_mfma_f32_16x16x32_bf16 v[68:71], v[176:179], v[216:219], v[68:71]
	v_mfma_f32_16x16x32_bf16 v[64:67], v[184:187], v[216:219], v[64:67]
	s_barrier
	s_add_i32 m0, s36, 0x10000
	ds_read_b128 v[188:191], v242 offset:16384
	ds_read_b128 v[192:195], v242 offset:17408
	ds_read_b128 v[196:199], v242 offset:18432
	ds_read_b128 v[200:203], v242 offset:19456
	ds_read_b128 v[204:207], v242 offset:20480
	ds_read_b128 v[208:211], v242 offset:21504
	ds_read_b128 v[212:215], v242 offset:22528
	ds_read_b128 v[216:219], v242 offset:23552
	global_load_lds_dwordx4 v150, vcc
	s_add_i32 m0, s36, 0x12000
	s_nop 0
	global_load_lds_dwordx4 v154, vcc
	s_add_i32 m0, s36, 0x14000
	s_nop 0
	global_load_lds_dwordx4 v232, vcc
	s_add_i32 m0, s36, 0x16000
	s_nop 0
	global_load_lds_dwordx4 v233, vcc
	s_mov_b32 m0, s37
	s_nop 0
	global_load_lds_dwordx4 v148, s[2:3]
	s_mov_b32 m0, s42
	s_nop 0
	global_load_lds_dwordx4 v152, s[2:3]
	s_waitcnt vmcnt(8) lgkmcnt(0)
	s_barrier
	v_mfma_f32_16x16x32_bf16 v[60:63], v[128:131], v[188:191], v[60:63]
	v_mfma_f32_16x16x32_bf16 v[56:59], v[136:139], v[188:191], v[56:59]
	v_mfma_f32_16x16x32_bf16 v[44:47], v[128:131], v[196:199], v[44:47]
	v_mfma_f32_16x16x32_bf16 v[40:43], v[136:139], v[196:199], v[40:43]
	v_mfma_f32_16x16x32_bf16 v[28:31], v[128:131], v[204:207], v[28:31]
	v_mfma_f32_16x16x32_bf16 v[24:27], v[136:139], v[204:207], v[24:27]
	v_mfma_f32_16x16x32_bf16 v[12:15], v[128:131], v[212:215], v[12:15]
	v_mfma_f32_16x16x32_bf16 v[8:11], v[136:139], v[212:215], v[8:11]
	v_mfma_f32_16x16x32_bf16 v[60:63], v[132:135], v[192:195], v[60:63]
	v_mfma_f32_16x16x32_bf16 v[56:59], v[140:143], v[192:195], v[56:59]
	v_mfma_f32_16x16x32_bf16 v[44:47], v[132:135], v[200:203], v[44:47]
	v_mfma_f32_16x16x32_bf16 v[40:43], v[140:143], v[200:203], v[40:43]
	v_mfma_f32_16x16x32_bf16 v[28:31], v[132:135], v[208:211], v[28:31]
	v_mfma_f32_16x16x32_bf16 v[24:27], v[140:143], v[208:211], v[24:27]
	v_mfma_f32_16x16x32_bf16 v[12:15], v[132:135], v[216:219], v[12:15]
	v_mfma_f32_16x16x32_bf16 v[8:11], v[140:143], v[216:219], v[8:11]
	v_mfma_f32_16x16x32_bf16 v[52:55], v[166:169], v[188:191], v[52:55]
	v_mfma_f32_16x16x32_bf16 v[48:51], v[180:183], v[188:191], v[48:51]
	v_mfma_f32_16x16x32_bf16 v[36:39], v[166:169], v[196:199], v[36:39]
	v_mfma_f32_16x16x32_bf16 v[32:35], v[180:183], v[196:199], v[32:35]
	v_mfma_f32_16x16x32_bf16 v[20:23], v[166:169], v[204:207], v[20:23]
	v_mfma_f32_16x16x32_bf16 v[16:19], v[180:183], v[204:207], v[16:19]
	v_mfma_f32_16x16x32_bf16 v[4:7], v[166:169], v[212:215], v[4:7]
	v_mfma_f32_16x16x32_bf16 v[0:3], v[180:183], v[212:215], v[0:3]
	v_mfma_f32_16x16x32_bf16 v[52:55], v[176:179], v[192:195], v[52:55]
	v_mfma_f32_16x16x32_bf16 v[48:51], v[184:187], v[192:195], v[48:51]
	v_mfma_f32_16x16x32_bf16 v[36:39], v[176:179], v[200:203], v[36:39]
	v_mfma_f32_16x16x32_bf16 v[32:35], v[184:187], v[200:203], v[32:35]
	v_mfma_f32_16x16x32_bf16 v[20:23], v[176:179], v[208:211], v[20:23]
	v_mfma_f32_16x16x32_bf16 v[16:19], v[184:187], v[208:211], v[16:19]
	v_mfma_f32_16x16x32_bf16 v[4:7], v[176:179], v[216:219], v[4:7]
	v_mfma_f32_16x16x32_bf16 v[0:3], v[184:187], v[216:219], v[0:3]
	s_barrier
	ds_read_b128 v[128:131], v170 offset:32768
	ds_read_b128 v[132:135], v170 offset:33792
	ds_read_b128 v[136:139], v170 offset:34816
	ds_read_b128 v[140:143], v170 offset:35840
	ds_read_b128 v[166:169], v170 offset:49152
	ds_read_b128 v[176:179], v170 offset:50176
	ds_read_b128 v[180:183], v170 offset:51200
	ds_read_b128 v[184:187], v170 offset:52224
	s_mov_b32 m0, s43
	ds_read_b128 v[188:191], v242 offset:32768
	ds_read_b128 v[192:195], v242 offset:33792
	ds_read_b128 v[196:199], v242 offset:34816
	ds_read_b128 v[200:203], v242 offset:35840
	ds_read_b128 v[204:207], v242 offset:36864
	ds_read_b128 v[208:211], v242 offset:37888
	ds_read_b128 v[212:215], v242 offset:38912
	ds_read_b128 v[216:219], v242 offset:39936
	global_load_lds_dwordx4 v234, s[2:3]
	s_mov_b32 m0, s16
	s_nop 0
	global_load_lds_dwordx4 v235, s[2:3]
	s_waitcnt vmcnt(8) lgkmcnt(0)
	s_barrier
	v_mfma_f32_16x16x32_bf16 v[124:127], v[128:131], v[188:191], v[124:127]
	v_mfma_f32_16x16x32_bf16 v[120:123], v[136:139], v[188:191], v[120:123]
	v_mfma_f32_16x16x32_bf16 v[108:111], v[128:131], v[196:199], v[108:111]
	v_mfma_f32_16x16x32_bf16 v[104:107], v[136:139], v[196:199], v[104:107]
	v_mfma_f32_16x16x32_bf16 v[92:95], v[128:131], v[204:207], v[92:95]
	v_mfma_f32_16x16x32_bf16 v[88:91], v[136:139], v[204:207], v[88:91]
	v_mfma_f32_16x16x32_bf16 v[76:79], v[128:131], v[212:215], v[76:79]
	v_mfma_f32_16x16x32_bf16 v[72:75], v[136:139], v[212:215], v[72:75]
	v_mfma_f32_16x16x32_bf16 v[124:127], v[132:135], v[192:195], v[124:127]
	v_mfma_f32_16x16x32_bf16 v[120:123], v[140:143], v[192:195], v[120:123]
	v_mfma_f32_16x16x32_bf16 v[108:111], v[132:135], v[200:203], v[108:111]
	v_mfma_f32_16x16x32_bf16 v[104:107], v[140:143], v[200:203], v[104:107]
	v_mfma_f32_16x16x32_bf16 v[92:95], v[132:135], v[208:211], v[92:95]
	v_mfma_f32_16x16x32_bf16 v[88:91], v[140:143], v[208:211], v[88:91]
	v_mfma_f32_16x16x32_bf16 v[76:79], v[132:135], v[216:219], v[76:79]
	v_mfma_f32_16x16x32_bf16 v[72:75], v[140:143], v[216:219], v[72:75]
	v_mfma_f32_16x16x32_bf16 v[116:119], v[166:169], v[188:191], v[116:119]
	v_mfma_f32_16x16x32_bf16 v[112:115], v[180:183], v[188:191], v[112:115]
	v_mfma_f32_16x16x32_bf16 v[100:103], v[166:169], v[196:199], v[100:103]
	v_mfma_f32_16x16x32_bf16 v[96:99], v[180:183], v[196:199], v[96:99]
	v_mfma_f32_16x16x32_bf16 v[84:87], v[166:169], v[204:207], v[84:87]
	v_mfma_f32_16x16x32_bf16 v[80:83], v[180:183], v[204:207], v[80:83]
	v_mfma_f32_16x16x32_bf16 v[68:71], v[166:169], v[212:215], v[68:71]
	v_mfma_f32_16x16x32_bf16 v[64:67], v[180:183], v[212:215], v[64:67]
	v_mfma_f32_16x16x32_bf16 v[116:119], v[176:179], v[192:195], v[116:119]
	v_mfma_f32_16x16x32_bf16 v[112:115], v[184:187], v[192:195], v[112:115]
	v_mfma_f32_16x16x32_bf16 v[100:103], v[176:179], v[200:203], v[100:103]
	v_mfma_f32_16x16x32_bf16 v[96:99], v[184:187], v[200:203], v[96:99]
	v_mfma_f32_16x16x32_bf16 v[84:87], v[176:179], v[208:211], v[84:87]
	v_mfma_f32_16x16x32_bf16 v[80:83], v[184:187], v[208:211], v[80:83]
	v_mfma_f32_16x16x32_bf16 v[68:71], v[176:179], v[216:219], v[68:71]
	v_mfma_f32_16x16x32_bf16 v[64:67], v[184:187], v[216:219], v[64:67]
	s_barrier
	s_add_i32 m0, s36, 0x18000
	ds_read_b128 v[188:191], v242 offset:49152
	ds_read_b128 v[192:195], v242 offset:50176
	ds_read_b128 v[196:199], v242 offset:51200
	ds_read_b128 v[200:203], v242 offset:52224
	ds_read_b128 v[204:207], v242 offset:53248
	ds_read_b128 v[208:211], v242 offset:54272
	ds_read_b128 v[212:215], v242 offset:55296
	ds_read_b128 v[216:219], v242 offset:56320
	s_add_u32 vcc_lo, vcc_lo, 0x80
	s_addc_u32 vcc_hi, vcc_hi, 0
	global_load_lds_dwordx4 v150, vcc
	s_add_i32 m0, s36, 0x1a000
	s_add_u32 s2, s2, 0x80
	s_addc_u32 s3, s3, 0
	global_load_lds_dwordx4 v154, vcc
	s_add_i32 m0, s36, 0x1c000
	s_nop 0
	global_load_lds_dwordx4 v232, vcc
	s_add_i32 m0, s36, 0x1e000
	s_add_u32 s0, s0, 0x100
	s_addc_u32 s1, s1, 0
	global_load_lds_dwordx4 v233, vcc
	s_mov_b32 m0, s63
	s_add_u32 s11, s11, 0x100
	s_addc_u32 s24, s24, 0
	global_load_lds_dwordx4 v148, s[2:3]
	s_mov_b32 m0, s18
	s_nop 0
	global_load_lds_dwordx4 v152, s[2:3]
	s_waitcnt vmcnt(8) lgkmcnt(0)
	s_barrier
	v_mfma_f32_16x16x32_bf16 v[60:63], v[128:131], v[188:191], v[60:63]
	v_mfma_f32_16x16x32_bf16 v[56:59], v[136:139], v[188:191], v[56:59]
	v_mfma_f32_16x16x32_bf16 v[44:47], v[128:131], v[196:199], v[44:47]
	v_mfma_f32_16x16x32_bf16 v[40:43], v[136:139], v[196:199], v[40:43]
	v_mfma_f32_16x16x32_bf16 v[28:31], v[128:131], v[204:207], v[28:31]
	v_mfma_f32_16x16x32_bf16 v[24:27], v[136:139], v[204:207], v[24:27]
	v_mfma_f32_16x16x32_bf16 v[12:15], v[128:131], v[212:215], v[12:15]
	v_mfma_f32_16x16x32_bf16 v[8:11], v[136:139], v[212:215], v[8:11]
	v_mfma_f32_16x16x32_bf16 v[60:63], v[132:135], v[192:195], v[60:63]
	v_mfma_f32_16x16x32_bf16 v[56:59], v[140:143], v[192:195], v[56:59]
	v_mfma_f32_16x16x32_bf16 v[44:47], v[132:135], v[200:203], v[44:47]
	v_mfma_f32_16x16x32_bf16 v[40:43], v[140:143], v[200:203], v[40:43]
	v_mfma_f32_16x16x32_bf16 v[28:31], v[132:135], v[208:211], v[28:31]
	v_mfma_f32_16x16x32_bf16 v[24:27], v[140:143], v[208:211], v[24:27]
	v_mfma_f32_16x16x32_bf16 v[12:15], v[132:135], v[216:219], v[12:15]
	v_mfma_f32_16x16x32_bf16 v[8:11], v[140:143], v[216:219], v[8:11]
	v_mfma_f32_16x16x32_bf16 v[52:55], v[166:169], v[188:191], v[52:55]
	v_mfma_f32_16x16x32_bf16 v[48:51], v[180:183], v[188:191], v[48:51]
	v_mfma_f32_16x16x32_bf16 v[36:39], v[166:169], v[196:199], v[36:39]
	v_mfma_f32_16x16x32_bf16 v[32:35], v[180:183], v[196:199], v[32:35]
	v_mfma_f32_16x16x32_bf16 v[20:23], v[166:169], v[204:207], v[20:23]
	v_mfma_f32_16x16x32_bf16 v[16:19], v[180:183], v[204:207], v[16:19]
	v_mfma_f32_16x16x32_bf16 v[4:7], v[166:169], v[212:215], v[4:7]
	v_mfma_f32_16x16x32_bf16 v[0:3], v[180:183], v[212:215], v[0:3]
	v_mfma_f32_16x16x32_bf16 v[52:55], v[176:179], v[192:195], v[52:55]
	v_mfma_f32_16x16x32_bf16 v[48:51], v[184:187], v[192:195], v[48:51]
	v_mfma_f32_16x16x32_bf16 v[36:39], v[176:179], v[200:203], v[36:39]
	v_mfma_f32_16x16x32_bf16 v[32:35], v[184:187], v[200:203], v[32:35]
	v_mfma_f32_16x16x32_bf16 v[20:23], v[176:179], v[208:211], v[20:23]
	v_mfma_f32_16x16x32_bf16 v[16:19], v[184:187], v[208:211], v[16:19]
	v_mfma_f32_16x16x32_bf16 v[4:7], v[176:179], v[216:219], v[4:7]
	v_mfma_f32_16x16x32_bf16 v[0:3], v[184:187], v[216:219], v[0:3]
	s_barrier
	s_cmp_ge_u32 s90, s60
	s_mov_b32 s2, s90
	s_cbranch_scc0 .LBB0_295
	s_branch .LBB0_297
